# cache policy: the FFN hidden-activation stores of the gate/up epilogue marked nt (streamed once, re-read only by the next phase) to keep weights/activations in L2 during the gate/up GEMM
# baseline (speedup 1.0000x reference)
; #define LAS __attribute__((address_space(3)))
; __device__ __forceinline__ unsigned pk2(float lo, float hi) { f32x2 v = {lo, hi}; bf16x2_t b = __builtin_convertvector(v, bf16x2_t); return __builtin_bit_cast(unsigned, b); }
; __device__ __forceinline__ float silu_f(float g) { return g * __builtin_amdgcn_rcpf(1.f + __builtin_amdgcn_exp2f(g * -1.4426950408889634f)); }
;     __device__ __forceinline__ void operator()(const f32x4 (&acc)[2][2][4][2], const Unit& u, int wr, int wc, int fr, int fq, LAS unsigned char* lds, int tid, State& st) const {
;         const int row0 = u.pm * BM + wr * 64 + fr, col0 = u.pn * 128 + wc * 32 + 8 * fq;
;         const LAS float* RT = rstd_panel(st, lds, u.pm, tid);
; #pragma unroll
;         for (int ai = 0; ai < 2; ++ai) {
;             float rs[4];
; #pragma unroll
;             for (int m = 0; m < 4; ++m) rs[m] = RT[wr * 64 + fr + ai * HALF + m * 16];
; #pragma unroll
;             for (int m = 0; m < 4; ++m) {
;                 const int row = row0 + ai * HALF + m * 16; const float r = rs[m];
;                 const f32x4 g0 = acc[ai][0][m][0] * r, g1 = acc[ai][0][m][1] * r, u0 = acc[ai][1][m][0] * r, u1 = acc[ai][1][m][1] * r;
;                 u32x4 w;
;                 w.x = pk2(silu_f(g0[0]) * u0[0], silu_f(g0[1]) * u0[1]); w.y = pk2(silu_f(g0[2]) * u0[2], silu_f(g0[3]) * u0[3]);
;                 w.z = pk2(silu_f(g1[0]) * u1[0], silu_f(g1[1]) * u1[1]); w.w = pk2(silu_f(g1[2]) * u1[2], silu_f(g1[3]) * u1[3]);
;                 *(u32x4*)(H + (size_t)row * DFF + col0) = w;
.LBB0_725:
	ds_read2_b32 v[154:155], v150 offset1:16
	ds_read2_b32 v[142:143], v150 offset0:32 offset1:48
	ds_read2_b32 v[156:157], v150 offset0:128 offset1:144
	ds_read2_b32 v[144:145], v150 offset0:160 offset1:176
	s_andn2_b64 vcc, exec, s[42:43]
	v_lshl_or_b32 v216, s21, 7, v151
	v_lshl_add_u32 v217, s9, 8, v147
	v_mov_b32_e32 v204, 1.0
	v_mul_u32_u24_e32 v214, 0x1600, v217
	v_lshl_add_u32 v214, v216, 1, v214
	s_waitcnt lgkmcnt(0)
	v_mul_f32_e32 v200, 0xbfb8aa3b, v154
	v_mul_f32_e32 v202, v154, v154
	v_mov_b32_e32 v215, v214
	v_pk_mul_f32 v[206:207], v[128:129], v[200:201] op_sel_hi:[1,0]
	v_pk_mul_f32 v[208:209], v[130:131], v[200:201] op_sel_hi:[1,0]
	v_pk_mul_f32 v[210:211], v[124:125], v[200:201] op_sel_hi:[1,0]
	v_pk_mul_f32 v[212:213], v[126:127], v[200:201] op_sel_hi:[1,0]
	v_exp_f32_e32 v206, v206
	v_exp_f32_e32 v207, v207
	v_exp_f32_e32 v208, v208
	v_exp_f32_e32 v209, v209
	v_exp_f32_e32 v210, v210
	v_exp_f32_e32 v211, v211
	v_exp_f32_e32 v212, v212
	v_exp_f32_e32 v213, v213
	v_pk_mul_f32 v[120:121], v[128:129], v[120:121]
	v_pk_mul_f32 v[122:123], v[130:131], v[122:123]
	v_pk_mul_f32 v[116:117], v[124:125], v[116:117]
	v_pk_mul_f32 v[118:119], v[126:127], v[118:119]
	v_pk_add_f32 v[206:207], v[206:207], v[204:205] op_sel_hi:[1,0]
	v_pk_add_f32 v[208:209], v[208:209], v[204:205] op_sel_hi:[1,0]
	v_pk_add_f32 v[210:211], v[210:211], v[204:205] op_sel_hi:[1,0]
	v_pk_add_f32 v[212:213], v[212:213], v[204:205] op_sel_hi:[1,0]
	v_rcp_f32_e32 v206, v206
	v_rcp_f32_e32 v207, v207
	v_rcp_f32_e32 v208, v208
	v_rcp_f32_e32 v209, v209
	v_rcp_f32_e32 v210, v210
	v_rcp_f32_e32 v211, v211
	v_rcp_f32_e32 v212, v212
	v_rcp_f32_e32 v213, v213
	v_pk_mul_f32 v[120:121], v[120:121], v[202:203] op_sel_hi:[1,0]
	v_pk_mul_f32 v[122:123], v[122:123], v[202:203] op_sel_hi:[1,0]
	v_pk_mul_f32 v[116:117], v[116:117], v[202:203] op_sel_hi:[1,0]
	v_pk_mul_f32 v[118:119], v[118:119], v[202:203] op_sel_hi:[1,0]
	v_pk_mul_f32 v[120:121], v[120:121], v[206:207]
	v_pk_mul_f32 v[122:123], v[122:123], v[208:209]
	v_pk_mul_f32 v[116:117], v[116:117], v[210:211]
	v_pk_mul_f32 v[118:119], v[118:119], v[212:213]
	v_cvt_pk_bf16_f32 v120, v120, v121
	v_cvt_pk_bf16_f32 v121, v122, v123
	v_cvt_pk_bf16_f32 v122, v116, v117
	v_cvt_pk_bf16_f32 v123, v118, v119
	global_store_dwordx4 v215, v[120:123], s[94:95] nt
	v_mul_f32_e32 v200, 0xbfb8aa3b, v155
	v_mul_f32_e32 v202, v155, v155
	v_add_u32_e32 v215, 0x16000, v214
	v_pk_mul_f32 v[206:207], v[112:113], v[200:201] op_sel_hi:[1,0]
	v_pk_mul_f32 v[208:209], v[114:115], v[200:201] op_sel_hi:[1,0]
	v_pk_mul_f32 v[210:211], v[108:109], v[200:201] op_sel_hi:[1,0]
	v_pk_mul_f32 v[212:213], v[110:111], v[200:201] op_sel_hi:[1,0]
	v_exp_f32_e32 v206, v206
	v_exp_f32_e32 v207, v207
	v_exp_f32_e32 v208, v208
	v_exp_f32_e32 v209, v209
	v_exp_f32_e32 v210, v210
	v_exp_f32_e32 v211, v211
	v_exp_f32_e32 v212, v212
	v_exp_f32_e32 v213, v213
	v_pk_mul_f32 v[104:105], v[112:113], v[104:105]
	v_pk_mul_f32 v[106:107], v[114:115], v[106:107]
	v_pk_mul_f32 v[100:101], v[108:109], v[100:101]
	v_pk_mul_f32 v[102:103], v[110:111], v[102:103]
	v_pk_add_f32 v[206:207], v[206:207], v[204:205] op_sel_hi:[1,0]
	v_pk_add_f32 v[208:209], v[208:209], v[204:205] op_sel_hi:[1,0]
	v_pk_add_f32 v[210:211], v[210:211], v[204:205] op_sel_hi:[1,0]
	v_pk_add_f32 v[212:213], v[212:213], v[204:205] op_sel_hi:[1,0]
	v_rcp_f32_e32 v206, v206
	v_rcp_f32_e32 v207, v207
	v_rcp_f32_e32 v208, v208
	v_rcp_f32_e32 v209, v209
	v_rcp_f32_e32 v210, v210
	v_rcp_f32_e32 v211, v211
	v_rcp_f32_e32 v212, v212
	v_rcp_f32_e32 v213, v213
	v_pk_mul_f32 v[104:105], v[104:105], v[202:203] op_sel_hi:[1,0]
	v_pk_mul_f32 v[106:107], v[106:107], v[202:203] op_sel_hi:[1,0]
	v_pk_mul_f32 v[100:101], v[100:101], v[202:203] op_sel_hi:[1,0]
	v_pk_mul_f32 v[102:103], v[102:103], v[202:203] op_sel_hi:[1,0]
	v_pk_mul_f32 v[104:105], v[104:105], v[206:207]
	v_pk_mul_f32 v[106:107], v[106:107], v[208:209]
	v_pk_mul_f32 v[100:101], v[100:101], v[210:211]
	v_pk_mul_f32 v[102:103], v[102:103], v[212:213]
	v_cvt_pk_bf16_f32 v104, v104, v105
	v_cvt_pk_bf16_f32 v105, v106, v107
	v_cvt_pk_bf16_f32 v106, v100, v101
	v_cvt_pk_bf16_f32 v107, v102, v103
	global_store_dwordx4 v215, v[104:107], s[94:95] nt
	v_mul_f32_e32 v200, 0xbfb8aa3b, v142
	v_mul_f32_e32 v202, v142, v142
	v_add_u32_e32 v215, 0x2c000, v214
	v_pk_mul_f32 v[206:207], v[96:97], v[200:201] op_sel_hi:[1,0]
	v_pk_mul_f32 v[208:209], v[98:99], v[200:201] op_sel_hi:[1,0]
	v_pk_mul_f32 v[210:211], v[92:93], v[200:201] op_sel_hi:[1,0]
	v_pk_mul_f32 v[212:213], v[94:95], v[200:201] op_sel_hi:[1,0]
	v_exp_f32_e32 v206, v206
	v_exp_f32_e32 v207, v207
	v_exp_f32_e32 v208, v208
	v_exp_f32_e32 v209, v209
	v_exp_f32_e32 v210, v210
	v_exp_f32_e32 v211, v211
	v_exp_f32_e32 v212, v212
	v_exp_f32_e32 v213, v213
	v_pk_mul_f32 v[88:89], v[96:97], v[88:89]
	v_pk_mul_f32 v[90:91], v[98:99], v[90:91]
	v_pk_mul_f32 v[84:85], v[92:93], v[84:85]
	v_pk_mul_f32 v[86:87], v[94:95], v[86:87]
	v_pk_add_f32 v[206:207], v[206:207], v[204:205] op_sel_hi:[1,0]
	v_pk_add_f32 v[208:209], v[208:209], v[204:205] op_sel_hi:[1,0]
	v_pk_add_f32 v[210:211], v[210:211], v[204:205] op_sel_hi:[1,0]
	v_pk_add_f32 v[212:213], v[212:213], v[204:205] op_sel_hi:[1,0]
	v_rcp_f32_e32 v206, v206
	v_rcp_f32_e32 v207, v207
	v_rcp_f32_e32 v208, v208
	v_rcp_f32_e32 v209, v209
	v_rcp_f32_e32 v210, v210
	v_rcp_f32_e32 v211, v211
	v_rcp_f32_e32 v212, v212
	v_rcp_f32_e32 v213, v213
	v_pk_mul_f32 v[88:89], v[88:89], v[202:203] op_sel_hi:[1,0]
	v_pk_mul_f32 v[90:91], v[90:91], v[202:203] op_sel_hi:[1,0]
	v_pk_mul_f32 v[84:85], v[84:85], v[202:203] op_sel_hi:[1,0]
	v_pk_mul_f32 v[86:87], v[86:87], v[202:203] op_sel_hi:[1,0]
; __device__ __forceinline__ unsigned pk2(float lo, float hi) { f32x2 v = {lo, hi}; bf16x2_t b = __builtin_convertvector(v, bf16x2_t); return __builtin_bit_cast(unsigned, b); }
; __device__ __forceinline__ float silu_f(float g) { return g * __builtin_amdgcn_rcpf(1.f + __builtin_amdgcn_exp2f(g * -1.4426950408889634f)); }
;     __device__ __forceinline__ void operator()(const f32x4 (&acc)[2][2][4][2], const Unit& u, int wr, int wc, int fr, int fq, LAS unsigned char* lds, int tid, State& st) const {
;     ...
;             for (int m = 0; m < 4; ++m) {
;                 const int row = row0 + ai * HALF + m * 16; const float r = rs[m];
;                 const f32x4 g0 = acc[ai][0][m][0] * r, g1 = acc[ai][0][m][1] * r, u0 = acc[ai][1][m][0] * r, u1 = acc[ai][1][m][1] * r;
;                 u32x4 w;
;                 w.x = pk2(silu_f(g0[0]) * u0[0], silu_f(g0[1]) * u0[1]); w.y = pk2(silu_f(g0[2]) * u0[2], silu_f(g0[3]) * u0[3]);
;                 w.z = pk2(silu_f(g1[0]) * u1[0], silu_f(g1[1]) * u1[1]); w.w = pk2(silu_f(g1[2]) * u1[2], silu_f(g1[3]) * u1[3]);
;                 *(u32x4*)(H + (size_t)row * DFF + col0) = w;
	v_pk_mul_f32 v[88:89], v[88:89], v[206:207]
	v_pk_mul_f32 v[90:91], v[90:91], v[208:209]
	v_pk_mul_f32 v[84:85], v[84:85], v[210:211]
	v_pk_mul_f32 v[86:87], v[86:87], v[212:213]
	v_cvt_pk_bf16_f32 v88, v88, v89
	v_cvt_pk_bf16_f32 v89, v90, v91
	v_cvt_pk_bf16_f32 v90, v84, v85
	v_cvt_pk_bf16_f32 v91, v86, v87
	global_store_dwordx4 v215, v[88:91], s[94:95] nt
	v_mul_f32_e32 v200, 0xbfb8aa3b, v143
	v_mul_f32_e32 v202, v143, v143
	v_add_u32_e32 v215, 0x42000, v214
	v_pk_mul_f32 v[206:207], v[80:81], v[200:201] op_sel_hi:[1,0]
	v_pk_mul_f32 v[208:209], v[82:83], v[200:201] op_sel_hi:[1,0]
	v_pk_mul_f32 v[210:211], v[76:77], v[200:201] op_sel_hi:[1,0]
	v_pk_mul_f32 v[212:213], v[78:79], v[200:201] op_sel_hi:[1,0]
	v_exp_f32_e32 v206, v206
	v_exp_f32_e32 v207, v207
	v_exp_f32_e32 v208, v208
	v_exp_f32_e32 v209, v209
	v_exp_f32_e32 v210, v210
	v_exp_f32_e32 v211, v211
	v_exp_f32_e32 v212, v212
	v_exp_f32_e32 v213, v213
	v_pk_mul_f32 v[72:73], v[80:81], v[72:73]
	v_pk_mul_f32 v[74:75], v[82:83], v[74:75]
	v_pk_mul_f32 v[68:69], v[76:77], v[68:69]
	v_pk_mul_f32 v[70:71], v[78:79], v[70:71]
	v_pk_add_f32 v[206:207], v[206:207], v[204:205] op_sel_hi:[1,0]
	v_pk_add_f32 v[208:209], v[208:209], v[204:205] op_sel_hi:[1,0]
	v_pk_add_f32 v[210:211], v[210:211], v[204:205] op_sel_hi:[1,0]
	v_pk_add_f32 v[212:213], v[212:213], v[204:205] op_sel_hi:[1,0]
	v_rcp_f32_e32 v206, v206
	v_rcp_f32_e32 v207, v207
	v_rcp_f32_e32 v208, v208
	v_rcp_f32_e32 v209, v209
	v_rcp_f32_e32 v210, v210
	v_rcp_f32_e32 v211, v211
	v_rcp_f32_e32 v212, v212
	v_rcp_f32_e32 v213, v213
	v_pk_mul_f32 v[72:73], v[72:73], v[202:203] op_sel_hi:[1,0]
	v_pk_mul_f32 v[74:75], v[74:75], v[202:203] op_sel_hi:[1,0]
	v_pk_mul_f32 v[68:69], v[68:69], v[202:203] op_sel_hi:[1,0]
	v_pk_mul_f32 v[70:71], v[70:71], v[202:203] op_sel_hi:[1,0]
	v_pk_mul_f32 v[72:73], v[72:73], v[206:207]
	v_pk_mul_f32 v[74:75], v[74:75], v[208:209]
	v_pk_mul_f32 v[68:69], v[68:69], v[210:211]
	v_pk_mul_f32 v[70:71], v[70:71], v[212:213]
	v_cvt_pk_bf16_f32 v72, v72, v73
	v_cvt_pk_bf16_f32 v73, v74, v75
	v_cvt_pk_bf16_f32 v74, v68, v69
	v_cvt_pk_bf16_f32 v75, v70, v71
	global_store_dwordx4 v215, v[72:75], s[94:95] nt
	v_mul_f32_e32 v200, 0xbfb8aa3b, v156
	v_mul_f32_e32 v202, v156, v156
	v_add_u32_e32 v215, 0xb0000, v214
	v_pk_mul_f32 v[206:207], v[64:65], v[200:201] op_sel_hi:[1,0]
	v_pk_mul_f32 v[208:209], v[66:67], v[200:201] op_sel_hi:[1,0]
	v_pk_mul_f32 v[210:211], v[60:61], v[200:201] op_sel_hi:[1,0]
	v_pk_mul_f32 v[212:213], v[62:63], v[200:201] op_sel_hi:[1,0]
	v_exp_f32_e32 v206, v206
	v_exp_f32_e32 v207, v207
	v_exp_f32_e32 v208, v208
	v_exp_f32_e32 v209, v209
	v_exp_f32_e32 v210, v210
	v_exp_f32_e32 v211, v211
	v_exp_f32_e32 v212, v212
	v_exp_f32_e32 v213, v213
	v_pk_mul_f32 v[56:57], v[64:65], v[56:57]
	v_pk_mul_f32 v[58:59], v[66:67], v[58:59]
	v_pk_mul_f32 v[52:53], v[60:61], v[52:53]
	v_pk_mul_f32 v[54:55], v[62:63], v[54:55]
	v_pk_add_f32 v[206:207], v[206:207], v[204:205] op_sel_hi:[1,0]
	v_pk_add_f32 v[208:209], v[208:209], v[204:205] op_sel_hi:[1,0]
	v_pk_add_f32 v[210:211], v[210:211], v[204:205] op_sel_hi:[1,0]
	v_pk_add_f32 v[212:213], v[212:213], v[204:205] op_sel_hi:[1,0]
	v_rcp_f32_e32 v206, v206
	v_rcp_f32_e32 v207, v207
	v_rcp_f32_e32 v208, v208
	v_rcp_f32_e32 v209, v209
	v_rcp_f32_e32 v210, v210
	v_rcp_f32_e32 v211, v211
	v_rcp_f32_e32 v212, v212
	v_rcp_f32_e32 v213, v213
	v_pk_mul_f32 v[56:57], v[56:57], v[202:203] op_sel_hi:[1,0]
	v_pk_mul_f32 v[58:59], v[58:59], v[202:203] op_sel_hi:[1,0]
	v_pk_mul_f32 v[52:53], v[52:53], v[202:203] op_sel_hi:[1,0]
	v_pk_mul_f32 v[54:55], v[54:55], v[202:203] op_sel_hi:[1,0]
	v_pk_mul_f32 v[56:57], v[56:57], v[206:207]
	v_pk_mul_f32 v[58:59], v[58:59], v[208:209]
	v_pk_mul_f32 v[52:53], v[52:53], v[210:211]
	v_pk_mul_f32 v[54:55], v[54:55], v[212:213]
	v_cvt_pk_bf16_f32 v56, v56, v57
	v_cvt_pk_bf16_f32 v57, v58, v59
	v_cvt_pk_bf16_f32 v58, v52, v53
	v_cvt_pk_bf16_f32 v59, v54, v55
	global_store_dwordx4 v215, v[56:59], s[94:95] nt
	v_mul_f32_e32 v200, 0xbfb8aa3b, v157
	v_mul_f32_e32 v202, v157, v157
	v_add_u32_e32 v215, 0xc6000, v214
	v_pk_mul_f32 v[206:207], v[48:49], v[200:201] op_sel_hi:[1,0]
	v_pk_mul_f32 v[208:209], v[50:51], v[200:201] op_sel_hi:[1,0]
	v_pk_mul_f32 v[210:211], v[44:45], v[200:201] op_sel_hi:[1,0]
	v_pk_mul_f32 v[212:213], v[46:47], v[200:201] op_sel_hi:[1,0]
	v_exp_f32_e32 v206, v206
	v_exp_f32_e32 v207, v207
	v_exp_f32_e32 v208, v208
	v_exp_f32_e32 v209, v209
	v_exp_f32_e32 v210, v210
	v_exp_f32_e32 v211, v211
	v_exp_f32_e32 v212, v212
	v_exp_f32_e32 v213, v213
	v_pk_mul_f32 v[40:41], v[48:49], v[40:41]
	v_pk_mul_f32 v[42:43], v[50:51], v[42:43]
	v_pk_mul_f32 v[36:37], v[44:45], v[36:37]
	v_pk_mul_f32 v[38:39], v[46:47], v[38:39]
	v_pk_add_f32 v[206:207], v[206:207], v[204:205] op_sel_hi:[1,0]
	v_pk_add_f32 v[208:209], v[208:209], v[204:205] op_sel_hi:[1,0]
; __device__ __forceinline__ unsigned pk2(float lo, float hi) { f32x2 v = {lo, hi}; bf16x2_t b = __builtin_convertvector(v, bf16x2_t); return __builtin_bit_cast(unsigned, b); }
; __device__ __forceinline__ float silu_f(float g) { return g * __builtin_amdgcn_rcpf(1.f + __builtin_amdgcn_exp2f(g * -1.4426950408889634f)); }
;     __device__ __forceinline__ void unit_start(State& st, const Unit& u, int tid) const { rstd_unit_start(st, ssq, u.pm, tid); }
;     __device__ __forceinline__ void unit_start(State& st, const Unit& u, int tid) const { rstd_unit_start(st, ssq, u.pm, tid); }
;     __device__ __forceinline__ void operator()(const f32x4 (&acc)[2][2][4][2], const Unit& u, int wr, int wc, int fr, int fq, LAS unsigned char* lds, int tid, State& st) const {
;     ...
;             for (int m = 0; m < 4; ++m) {
;                 const int row = row0 + ai * HALF + m * 16; const float r = rs[m];
;                 const f32x4 g0 = acc[ai][0][m][0] * r, g1 = acc[ai][0][m][1] * r, u0 = acc[ai][1][m][0] * r, u1 = acc[ai][1][m][1] * r;
;                 u32x4 w;
;                 w.x = pk2(silu_f(g0[0]) * u0[0], silu_f(g0[1]) * u0[1]); w.y = pk2(silu_f(g0[2]) * u0[2], silu_f(g0[3]) * u0[3]);
;                 w.z = pk2(silu_f(g1[0]) * u1[0], silu_f(g1[1]) * u1[1]); w.w = pk2(silu_f(g1[2]) * u1[2], silu_f(g1[3]) * u1[3]);
;                 *(u32x4*)(H + (size_t)row * DFF + col0) = w;
; template <class Epi, class Sched>
; __device__ __forceinline__ void gemm_phase(LAS unsigned char* lds, const Gemm g, const Sched& S, const Epi& E) {
;     ...
;         E(acc, cur, wr, wc, fr, fq, lds, tid, est);
;         if (!has_next) break;
; #pragma unroll
;         for (int a = 0; a < 2; ++a)
; #pragma unroll
;             for (int b = 0; b < 2; ++b)
; #pragma unroll
;                 for (int m = 0; m < 4; ++m)
; #pragma unroll
;                     for (int n = 0; n < 2; ++n) acc[a][b][m][n] = (f32x4){0.f, 0.f, 0.f, 0.f};
;         cur = nxt; cA = nA; cB = nB; ++ui;
;         E.unit_start(est, cur, tid);
	v_pk_add_f32 v[210:211], v[210:211], v[204:205] op_sel_hi:[1,0]
	v_pk_add_f32 v[212:213], v[212:213], v[204:205] op_sel_hi:[1,0]
	v_rcp_f32_e32 v206, v206
	v_rcp_f32_e32 v207, v207
	v_rcp_f32_e32 v208, v208
	v_rcp_f32_e32 v209, v209
	v_rcp_f32_e32 v210, v210
	v_rcp_f32_e32 v211, v211
	v_rcp_f32_e32 v212, v212
	v_rcp_f32_e32 v213, v213
	v_pk_mul_f32 v[40:41], v[40:41], v[202:203] op_sel_hi:[1,0]
	v_pk_mul_f32 v[42:43], v[42:43], v[202:203] op_sel_hi:[1,0]
	v_pk_mul_f32 v[36:37], v[36:37], v[202:203] op_sel_hi:[1,0]
	v_pk_mul_f32 v[38:39], v[38:39], v[202:203] op_sel_hi:[1,0]
	v_pk_mul_f32 v[40:41], v[40:41], v[206:207]
	v_pk_mul_f32 v[42:43], v[42:43], v[208:209]
	v_pk_mul_f32 v[36:37], v[36:37], v[210:211]
	v_pk_mul_f32 v[38:39], v[38:39], v[212:213]
	v_cvt_pk_bf16_f32 v40, v40, v41
	v_cvt_pk_bf16_f32 v41, v42, v43
	v_cvt_pk_bf16_f32 v42, v36, v37
	v_cvt_pk_bf16_f32 v43, v38, v39
	global_store_dwordx4 v215, v[40:43], s[94:95] nt
	v_mul_f32_e32 v200, 0xbfb8aa3b, v144
	v_mul_f32_e32 v202, v144, v144
	v_add_u32_e32 v215, 0xdc000, v214
	v_pk_mul_f32 v[206:207], v[32:33], v[200:201] op_sel_hi:[1,0]
	v_pk_mul_f32 v[208:209], v[34:35], v[200:201] op_sel_hi:[1,0]
	v_pk_mul_f32 v[210:211], v[28:29], v[200:201] op_sel_hi:[1,0]
	v_pk_mul_f32 v[212:213], v[30:31], v[200:201] op_sel_hi:[1,0]
	v_exp_f32_e32 v206, v206
	v_exp_f32_e32 v207, v207
	v_exp_f32_e32 v208, v208
	v_exp_f32_e32 v209, v209
	v_exp_f32_e32 v210, v210
	v_exp_f32_e32 v211, v211
	v_exp_f32_e32 v212, v212
	v_exp_f32_e32 v213, v213
	v_pk_mul_f32 v[24:25], v[32:33], v[24:25]
	v_pk_mul_f32 v[26:27], v[34:35], v[26:27]
	v_pk_mul_f32 v[20:21], v[28:29], v[20:21]
	v_pk_mul_f32 v[22:23], v[30:31], v[22:23]
	v_pk_add_f32 v[206:207], v[206:207], v[204:205] op_sel_hi:[1,0]
	v_pk_add_f32 v[208:209], v[208:209], v[204:205] op_sel_hi:[1,0]
	v_pk_add_f32 v[210:211], v[210:211], v[204:205] op_sel_hi:[1,0]
	v_pk_add_f32 v[212:213], v[212:213], v[204:205] op_sel_hi:[1,0]
	v_rcp_f32_e32 v206, v206
	v_rcp_f32_e32 v207, v207
	v_rcp_f32_e32 v208, v208
	v_rcp_f32_e32 v209, v209
	v_rcp_f32_e32 v210, v210
	v_rcp_f32_e32 v211, v211
	v_rcp_f32_e32 v212, v212
	v_rcp_f32_e32 v213, v213
	v_pk_mul_f32 v[24:25], v[24:25], v[202:203] op_sel_hi:[1,0]
	v_pk_mul_f32 v[26:27], v[26:27], v[202:203] op_sel_hi:[1,0]
	v_pk_mul_f32 v[20:21], v[20:21], v[202:203] op_sel_hi:[1,0]
	v_pk_mul_f32 v[22:23], v[22:23], v[202:203] op_sel_hi:[1,0]
	v_pk_mul_f32 v[24:25], v[24:25], v[206:207]
	v_pk_mul_f32 v[26:27], v[26:27], v[208:209]
	v_pk_mul_f32 v[20:21], v[20:21], v[210:211]
	v_pk_mul_f32 v[22:23], v[22:23], v[212:213]
	v_cvt_pk_bf16_f32 v24, v24, v25
	v_cvt_pk_bf16_f32 v25, v26, v27
	v_cvt_pk_bf16_f32 v26, v20, v21
	v_cvt_pk_bf16_f32 v27, v22, v23
	global_store_dwordx4 v215, v[24:27], s[94:95] nt
	v_mul_f32_e32 v200, 0xbfb8aa3b, v145
	v_mul_f32_e32 v202, v145, v145
	v_add_u32_e32 v215, 0xf2000, v214
	v_pk_mul_f32 v[206:207], v[16:17], v[200:201] op_sel_hi:[1,0]
	v_pk_mul_f32 v[208:209], v[18:19], v[200:201] op_sel_hi:[1,0]
	v_pk_mul_f32 v[210:211], v[12:13], v[200:201] op_sel_hi:[1,0]
	v_pk_mul_f32 v[212:213], v[14:15], v[200:201] op_sel_hi:[1,0]
	v_exp_f32_e32 v206, v206
	v_exp_f32_e32 v207, v207
	v_exp_f32_e32 v208, v208
	v_exp_f32_e32 v209, v209
	v_exp_f32_e32 v210, v210
	v_exp_f32_e32 v211, v211
	v_exp_f32_e32 v212, v212
	v_exp_f32_e32 v213, v213
	v_pk_mul_f32 v[8:9], v[16:17], v[8:9]
	v_pk_mul_f32 v[10:11], v[18:19], v[10:11]
	v_pk_mul_f32 v[4:5], v[12:13], v[4:5]
	v_pk_mul_f32 v[6:7], v[14:15], v[6:7]
	v_pk_add_f32 v[206:207], v[206:207], v[204:205] op_sel_hi:[1,0]
	v_pk_add_f32 v[208:209], v[208:209], v[204:205] op_sel_hi:[1,0]
	v_pk_add_f32 v[210:211], v[210:211], v[204:205] op_sel_hi:[1,0]
	v_pk_add_f32 v[212:213], v[212:213], v[204:205] op_sel_hi:[1,0]
	v_rcp_f32_e32 v206, v206
	v_rcp_f32_e32 v207, v207
	v_rcp_f32_e32 v208, v208
	v_rcp_f32_e32 v209, v209
	v_rcp_f32_e32 v210, v210
	v_rcp_f32_e32 v211, v211
	v_rcp_f32_e32 v212, v212
	v_rcp_f32_e32 v213, v213
	v_pk_mul_f32 v[8:9], v[8:9], v[202:203] op_sel_hi:[1,0]
	v_pk_mul_f32 v[10:11], v[10:11], v[202:203] op_sel_hi:[1,0]
	v_pk_mul_f32 v[4:5], v[4:5], v[202:203] op_sel_hi:[1,0]
	v_pk_mul_f32 v[6:7], v[6:7], v[202:203] op_sel_hi:[1,0]
	v_pk_mul_f32 v[8:9], v[8:9], v[206:207]
	v_pk_mul_f32 v[10:11], v[10:11], v[208:209]
	v_pk_mul_f32 v[4:5], v[4:5], v[210:211]
	v_pk_mul_f32 v[6:7], v[6:7], v[212:213]
	v_cvt_pk_bf16_f32 v8, v8, v9
	v_cvt_pk_bf16_f32 v9, v10, v11
	v_cvt_pk_bf16_f32 v10, v4, v5
	v_cvt_pk_bf16_f32 v11, v6, v7
	global_store_dwordx4 v215, v[8:11], s[94:95] nt
	s_mov_b64 s[6:7], -1
	s_cbranch_vccnz .LBB0_713
	s_cmp_lg_u32 s22, s9
	s_cselect_b64 s[6:7], -1, 0
	s_and_b64 s[14:15], s[38:39], s[6:7]
	s_and_saveexec_b64 s[6:7], s[14:15]
	s_cbranch_execz .LBB0_728
	s_nop 0
	v_lshl_add_u32 v0, s22, 8, v146
	v_ashrrev_i32_e32 v1, 31, v0
	v_lshl_add_u64 v[0:1], v[0:1], 4, s[88:89]
	global_load_dwordx4 v[0:3], v[0:1], off
